# attention: hand-pipelined kt loop for unmasked chunks; item outputs transposed through a wave-private LDS image for full-row stores
# speedup vs baseline: 1.0047x; 1.0047x over previous
; __device__ __forceinline__ unsigned cvt_pk_bf16(float lo, float hi) { unsigned r; asm("v_cvt_pk_bf16_f32 %0, %1, %2" : "=v"(r) : "v"(lo), "v"(hi)); return r; }
; __device__ __forceinline__ void attn_mfma(PP p, unsigned char* shm, int wv) {
;     ...
; #pragma unroll
;         for (int qi = 0; qi < 2; ++qi) {
;             const float lt = lrun[qi] + __shfl_xor(lrun[qi], 32);
;             const float inv = 1.0f / lt;
;             bf16_t* orow = att + (size_t)(qrow0 + 32 * qi + l31) * 512 + hq * 64;
; #pragma unroll
;             for (int db = 0; db < 2; ++db)
; #pragma unroll
;                 for (int g4 = 0; g4 < 4; ++g4) {
;                     u32x2 w; w.x = cvt_pk_bf16(oacc[db][qi][4 * g4] * inv, oacc[db][qi][4 * g4 + 1] * inv); w.y = cvt_pk_bf16(oacc[db][qi][4 * g4 + 2] * inv, oacc[db][qi][4 * g4 + 3] * inv);
;                     *(u32x2*)(orow + 32 * db + 8 * g4 + 4 * hl) = w;
;                 }
;         }
.LBB0_455:
	v_and_b32_e32 v67, 64, v195
	v_xor_b32_e32 v66, 32, v195
	v_add_u32_e32 v67, 64, v67
	v_cmp_lt_i32_e32 vcc, v66, v67
	s_lshl_b32 s6, s35, 1
	s_add_i32 s34, s34, s24
	v_cndmask_b32_e32 v66, v195, v66, vcc
	v_lshlrev_b32_e32 v70, 2, v66
	ds_bpermute_b32 v66, v70, v196
	ds_bpermute_b32 v220, v70, v1
	s_waitcnt lgkmcnt(0)
	v_add_f32_e32 v68, v196, v66
	v_add_f32_e32 v1, v1, v220
	v_div_scale_f32 v69, s[4:5], v68, v68, 1.0
	v_rcp_f32_e32 v71, v69
	v_div_scale_f32 v72, vcc, 1.0, v68, 1.0
	v_fma_f32 v73, -v69, v71, 1.0
	v_fmac_f32_e32 v71, v73, v71
	v_mul_f32_e32 v73, v72, v71
	v_fma_f32 v74, -v69, v73, v72
	v_fmac_f32_e32 v73, v74, v71
	v_fma_f32 v69, -v69, v73, v72
	v_div_fmas_f32 v69, v69, v71, v73
	v_div_fixup_f32 v71, v69, v68, 1.0
	v_div_scale_f32 v224, s[4:5], v1, v1, 1.0
	v_rcp_f32_e32 v225, v224
	v_div_scale_f32 v221, vcc, 1.0, v1, 1.0
	v_fma_f32 v223, -v224, v225, 1.0
	v_fmac_f32_e32 v225, v223, v225
	v_mul_f32_e32 v222, v221, v225
	v_fma_f32 v223, -v224, v222, v221
	v_fmac_f32_e32 v222, v223, v225
	v_fma_f32 v221, -v224, v222, v221
	v_div_fmas_f32 v221, v221, v225, v222
	v_div_fixup_f32 v1, v221, v1, 1.0
	s_lshl_b32 s20, s56, 7
	s_add_i32 s20, s20, 0x12000
	v_and_b32_e32 v232, 31, v195
	v_lshrrev_b32_e32 v233, 5, v195
	v_and_b32_e32 v234, 7, v232
	v_xor_b32_e32 v234, v234, v233
	v_lshlrev_b32_e32 v234, 4, v234
	v_lshl_add_u32 v234, v232, 7, v234
	v_add_u32_e32 v234, s20, v234
	v_xor_b32_e32 v235, 32, v234
	v_xor_b32_e32 v236, 64, v234
	v_xor_b32_e32 v237, 0x60, v234
	v_lshrrev_b32_e32 v238, 3, v195
	v_and_b32_e32 v239, 7, v195
	v_xor_b32_e32 v240, v239, v238
	v_lshlrev_b32_e32 v240, 4, v240
	v_lshl_add_u32 v240, v238, 7, v240
	v_add_u32_e32 v240, s20, v240
	v_and_b32_e32 v241, -32, v176
	v_or_b32_e32 v241, v241, v238
	v_lshlrev_b32_e32 v241, 10, v241
	v_lshl_add_u32 v241, v239, 4, v241
	v_add_u32_e32 v241, s6, v241
	v_readfirstlane_b32 s28, v168
	v_readfirstlane_b32 s29, v169
	s_sub_u32 s28, s28, 0x8000000
	s_subb_u32 s29, s29, 0
	v_mul_f32_e32 v34, v34, v71
	v_mul_f32_e32 v35, v35, v71
	v_mul_f32_e32 v36, v36, v71
	v_mul_f32_e32 v37, v37, v71
	v_mul_f32_e32 v38, v38, v71
	v_mul_f32_e32 v39, v39, v71
	v_mul_f32_e32 v40, v40, v71
	v_mul_f32_e32 v41, v41, v71
	v_cvt_pk_bf16_f32 v34, v34, v35
	v_cvt_pk_bf16_f32 v35, v36, v37
	v_cvt_pk_bf16_f32 v36, v38, v39
	v_cvt_pk_bf16_f32 v37, v40, v41
	s_nop 1
	v_permlane32_swap_b32_e32 v34, v36
	v_permlane32_swap_b32_e32 v35, v37
	ds_write_b128 v236, v[34:37]
	v_mul_f32_e32 v42, v42, v71
	v_mul_f32_e32 v43, v43, v71
	v_mul_f32_e32 v44, v44, v71
	v_mul_f32_e32 v45, v45, v71
	v_mul_f32_e32 v46, v46, v71
	v_mul_f32_e32 v47, v47, v71
	v_mul_f32_e32 v48, v48, v71
	v_mul_f32_e32 v49, v49, v71
	v_cvt_pk_bf16_f32 v42, v42, v43
	v_cvt_pk_bf16_f32 v43, v44, v45
	v_cvt_pk_bf16_f32 v44, v46, v47
	v_cvt_pk_bf16_f32 v45, v48, v49
	s_nop 1
	v_permlane32_swap_b32_e32 v42, v44
	v_permlane32_swap_b32_e32 v43, v45
	ds_write_b128 v237, v[42:45]
	v_mul_f32_e32 v50, v50, v71
	v_mul_f32_e32 v51, v51, v71
	v_mul_f32_e32 v52, v52, v71
	v_mul_f32_e32 v53, v53, v71
	v_mul_f32_e32 v54, v54, v71
	v_mul_f32_e32 v55, v55, v71
	v_mul_f32_e32 v56, v56, v71
	v_mul_f32_e32 v57, v57, v71
	v_cvt_pk_bf16_f32 v50, v50, v51
	v_cvt_pk_bf16_f32 v51, v52, v53
	v_cvt_pk_bf16_f32 v52, v54, v55
	v_cvt_pk_bf16_f32 v53, v56, v57
	s_nop 1
	v_permlane32_swap_b32_e32 v50, v52
	v_permlane32_swap_b32_e32 v51, v53
	ds_write_b128 v234, v[50:53]
	v_mul_f32_e32 v58, v58, v71
	v_mul_f32_e32 v59, v59, v71
	v_mul_f32_e32 v60, v60, v71
	v_mul_f32_e32 v61, v61, v71
	v_mul_f32_e32 v62, v62, v71
	v_mul_f32_e32 v63, v63, v71
	v_mul_f32_e32 v64, v64, v71
	v_mul_f32_e32 v65, v65, v71
	v_cvt_pk_bf16_f32 v58, v58, v59
	v_cvt_pk_bf16_f32 v59, v60, v61
	v_cvt_pk_bf16_f32 v60, v62, v63
	v_cvt_pk_bf16_f32 v61, v64, v65
	s_nop 1
	v_permlane32_swap_b32_e32 v58, v60
	v_permlane32_swap_b32_e32 v59, v61
	ds_write_b128 v235, v[58:61]
	v_mul_f32_e32 v18, v18, v1
	v_mul_f32_e32 v19, v19, v1
	v_mul_f32_e32 v20, v20, v1
	v_mul_f32_e32 v21, v21, v1
	v_mul_f32_e32 v22, v22, v1
	v_mul_f32_e32 v23, v23, v1
	v_mul_f32_e32 v24, v24, v1
	v_mul_f32_e32 v25, v25, v1
	v_cvt_pk_bf16_f32 v18, v18, v19
	v_cvt_pk_bf16_f32 v19, v20, v21
	v_cvt_pk_bf16_f32 v20, v22, v23
	v_cvt_pk_bf16_f32 v21, v24, v25
	s_nop 1
	v_permlane32_swap_b32_e32 v18, v20
	v_permlane32_swap_b32_e32 v19, v21
	ds_write_b128 v234, v[18:21] offset:4096
	v_mul_f32_e32 v26, v26, v1
	v_mul_f32_e32 v27, v27, v1
	v_mul_f32_e32 v28, v28, v1
	v_mul_f32_e32 v29, v29, v1
	v_mul_f32_e32 v30, v30, v1
	v_mul_f32_e32 v31, v31, v1
	v_mul_f32_e32 v32, v32, v1
	v_mul_f32_e32 v33, v33, v1
	v_cvt_pk_bf16_f32 v26, v26, v27
	v_cvt_pk_bf16_f32 v27, v28, v29
	v_cvt_pk_bf16_f32 v28, v30, v31
	v_cvt_pk_bf16_f32 v29, v32, v33
	s_nop 1
	v_permlane32_swap_b32_e32 v26, v28
	v_permlane32_swap_b32_e32 v27, v29
	ds_write_b128 v235, v[26:29] offset:4096
	v_mul_f32_e32 v2, v2, v1
	v_mul_f32_e32 v3, v3, v1
	v_mul_f32_e32 v4, v4, v1
	v_mul_f32_e32 v5, v5, v1
	v_mul_f32_e32 v6, v6, v1
	v_mul_f32_e32 v7, v7, v1
	v_mul_f32_e32 v8, v8, v1
	v_mul_f32_e32 v9, v9, v1
	v_cvt_pk_bf16_f32 v2, v2, v3
	v_cvt_pk_bf16_f32 v3, v4, v5
	v_cvt_pk_bf16_f32 v4, v6, v7
	v_cvt_pk_bf16_f32 v5, v8, v9
	s_nop 1
	v_permlane32_swap_b32_e32 v2, v4
	v_permlane32_swap_b32_e32 v3, v5
	ds_write_b128 v236, v[2:5] offset:4096
	v_mul_f32_e32 v10, v10, v1
	v_mul_f32_e32 v11, v11, v1
	v_mul_f32_e32 v12, v12, v1
	v_mul_f32_e32 v13, v13, v1
	v_mul_f32_e32 v14, v14, v1
	v_mul_f32_e32 v15, v15, v1
	v_mul_f32_e32 v16, v16, v1
	v_mul_f32_e32 v17, v17, v1
	v_cvt_pk_bf16_f32 v10, v10, v11
	v_cvt_pk_bf16_f32 v11, v12, v13
	v_cvt_pk_bf16_f32 v12, v14, v15
	v_cvt_pk_bf16_f32 v13, v16, v17
	s_nop 1
	v_permlane32_swap_b32_e32 v10, v12
	v_permlane32_swap_b32_e32 v11, v13
	ds_write_b128 v237, v[10:13] offset:4096
	ds_read_b128 v[66:69], v240
	ds_read_b128 v[70:73], v240 offset:1024
	ds_read_b128 v[74:77], v240 offset:2048
	ds_read_b128 v[78:81], v240 offset:3072
	ds_read_b128 v[130:133], v240 offset:4096
	ds_read_b128 v[134:137], v240 offset:5120
	ds_read_b128 v[138:141], v240 offset:6144
	ds_read_b128 v[142:145], v240 offset:7168
	v_add_u32_e32 v242, 0x2000, v241
	v_add_u32_e32 v243, 0x4000, v241
	v_add_u32_e32 v244, 0x6000, v241
	v_add_u32_e32 v245, 0x8000, v241
	v_add_u32_e32 v246, 0xa000, v241
	v_add_u32_e32 v247, 0xc000, v241
	v_add_u32_e32 v248, 0xe000, v241
	s_waitcnt lgkmcnt(7)
	global_store_dwordx4 v241, v[66:69], s[28:29]
	s_waitcnt lgkmcnt(6)
	global_store_dwordx4 v242, v[70:73], s[28:29]
	s_waitcnt lgkmcnt(5)
	global_store_dwordx4 v243, v[74:77], s[28:29]
	s_waitcnt lgkmcnt(4)
	global_store_dwordx4 v244, v[78:81], s[28:29]
	s_waitcnt lgkmcnt(3)
	global_store_dwordx4 v245, v[130:133], s[28:29]
	s_waitcnt lgkmcnt(2)
	global_store_dwordx4 v246, v[134:137], s[28:29]
	s_waitcnt lgkmcnt(1)
	global_store_dwordx4 v247, v[138:141], s[28:29]
	s_waitcnt lgkmcnt(0)
	global_store_dwordx4 v248, v[142:145], s[28:29]
	s_cmpk_gt_i32 s34, 0x1ff
	s_cbranch_scc1 .LBB0_489

; __device__ __forceinline__ void attn_mfma(PP p, unsigned char* shm, int wv) {
;     ...
;         while (ci < 5) {
;             const int cn = ATT_NEXT(ci);
;             if (cn < 5) { ATT_STAGE(par ^ 1); const int c2 = ATT_NEXT(cn); if (c2 < 5) ATT_GLOAD(c2); }
;             const bf16_t* Ks = (const bf16_t*)(shm + par * 36864);
;             const bf16_t* Vt = (const bf16_t*)(shm + par * 36864 + 18432);
;             const int kt_lo = (ci == 0 && qh == 1) ? 2 : 0, kt_hi = (ci == 2 && qh == 0) ? 2 : 4;
; #pragma unroll 1
;             for (int kt = kt_lo; kt < kt_hi; ++kt) {
.LBB0_460:
	s_cmp_eq_u32 s38, 0
	s_cselect_b64 s[16:17], -1, 0
	s_cmp_lg_u32 s38, 0
	s_cselect_b64 s[18:19], -1, 0
	s_and_b64 s[20:21], s[10:11], s[16:17]
	s_and_b64 s[20:21], s[20:21], exec
	s_cselect_b32 s40, 2, 0
	s_cmp_eq_u32 s38, 2
	s_cselect_b64 s[20:21], -1, 0
	s_and_b64 s[20:21], s[12:13], s[20:21]
	s_and_b64 s[20:21], s[20:21], exec
	s_cselect_b32 s41, 2, 4
	s_cmp_ge_u32 s40, s41
	s_cbranch_scc1 .LBB0_487
	s_mul_i32 s20, s6, 0x9000
	s_lshl_b32 s21, s40, 6
	s_or_b32 s21, s20, s21
	v_add_u32_e32 v199, s21, v187
	s_mul_i32 s21, s40, 0x1200
	s_add_i32 s20, s20, s21
	v_add_u32_e32 v200, s20, v188
	v_lshl_add_u32 v201, s40, 5, v189
	s_cmp_eq_u32 s38, 0
	s_cbranch_scc1 .LBB0_463
	s_cmp_eq_u32 s38, 2
	s_cbranch_scc1 .LBB0_463
	s_branch .Lattn_p_entry

; __device__ __forceinline__ void attn_mfma(PP p, unsigned char* shm, int wv) {
;     ...
;             for (int kt = kt_lo; kt < kt_hi; ++kt) {
;                 bf16x8 kf[4];
; #pragma unroll
;                 for (int st = 0; st < 4; ++st) kf[st] = *(const bf16x8*)(Ks + (32 * kt + l31) * 72 + 16 * st + 8 * hl);
;                 bf16x8 vf[2][2];
; #pragma unroll
;                 for (int db = 0; db < 2; ++db)
; #pragma unroll
;                     for (int s2 = 0; s2 < 2; ++s2) {
;                         const bf16_t* vp = Vt + (32 * db + l31) * 132 + 32 * kt + 16 * s2 + 4 * hl;
;                         const u32x2 lo = *(const u32x2*)vp, hi = *(const u32x2*)(vp + 8);
;                         u32x4 w; w.x = lo.x; w.y = lo.y; w.z = hi.x; w.w = hi.y;
;                         vf[db][s2] = __builtin_bit_cast(bf16x8, w);
;                     }
; #pragma unroll
;                 for (int qi = 0; qi < 2; ++qi) {
;                     f32x16 s;
; #pragma unroll
;                     for (int i = 0; i < 16; ++i) s[i] = 0.f;
;                     __builtin_amdgcn_s_setprio(1);
; #pragma unroll
;                     for (int st = 0; st < 4; ++st) s = __builtin_amdgcn_mfma_f32_32x32x16_bf16(kf[st], qf[qi][st], s, 0, 0, 0);
;                     __builtin_amdgcn_s_setprio(0);
;                     if (ci == 0 || ci == 2) {
;                         asm volatile("");
;                         const int dl = (ci == 0) ? (32 * kt + 4 * hl - (64 * qh + 32 * qi + l31)) : ((64 * qh + 32 * qi + l31) - 32 * kt - 4 * hl);
; #pragma unroll
;                         for (int i = 0; i < 16; ++i) {
;                             const int ki = 8 * (i >> 2) + (i & 3);
;                             const bool ok = (ci == 0) ? (dl + ki >= 0) : (dl - ki >= 0);
;                             s[i] = ok ? s[i] : -1e30f;
;                         }
;                     }
;                     float mx = s[0];
; #pragma unroll
;                     for (int i = 1; i < 16; ++i) mx = fmaxf(mx, s[i]);
;                     mx = fmaxf(mx, __shfl_xor(mx, 32));
;                     const float mnew = fmaxf(mrun[qi], mx * SC2);
;                     if (__builtin_amdgcn_ballot_w64(mnew > mrun[qi]) != 0ull) {
;                         const float alpha = __builtin_amdgcn_exp2f(mrun[qi] - mnew);
;                         lrun[qi] *= alpha;
; #pragma unroll
.Lattn_p_entry:
	ds_read_b128 v[158:161], v200
	ds_read_b128 v[154:157], v200 offset:32
	ds_read_b128 v[150:153], v200 offset:64
	ds_read_b128 v[146:149], v200 offset:96
	v_add_u32_e32 v200, 0x1200, v200
	s_add_i32 s20, s41, -1
	s_waitcnt vmcnt(4) lgkmcnt(3)
	v_mfma_f32_32x32x16_bf16 v[66:81], v[158:161], v[82:85], 0
	s_waitcnt lgkmcnt(2)
	v_mfma_f32_32x32x16_bf16 v[66:81], v[154:157], v[86:89], v[66:81]
	s_waitcnt lgkmcnt(1)
	v_mfma_f32_32x32x16_bf16 v[66:81], v[150:153], v[90:93], v[66:81]
	s_waitcnt lgkmcnt(0)
	v_mfma_f32_32x32x16_bf16 v[66:81], v[146:149], v[94:97], v[66:81]
	s_nop 4
	s_cmp_ge_u32 s40, s20
	s_cbranch_scc1 .Lattn_p_last
.Lattn_p_loop:
	v_add_u32_e32 v236, 0x2000, v199
	ds_read2_b64 v[142:145], v199 offset1:2
	ds_read2_b64 v[138:141], v199 offset0:4 offset1:6
	ds_read2_b64 v[134:137], v236 offset0:32 offset1:34
	ds_read2_b64 v[130:133], v236 offset0:36 offset1:38
	v_add_u32_e32 v199, 64, v199
	v_mfma_f32_32x32x16_bf16 v[220:235], v[158:161], v[98:101], 0
	v_max3_f32 v244, v66, v67, v68
	v_max3_f32 v245, v69, v70, v71
	v_max3_f32 v244, v244, v72, v73
	v_max3_f32 v245, v245, v74, v75
	v_max3_f32 v244, v244, v76, v77
	v_max3_f32 v245, v245, v78, v79
	v_mfma_f32_32x32x16_bf16 v[220:235], v[154:157], v[102:105], v[220:235]
	v_max3_f32 v244, v244, v80, v81
	v_max_f32_e32 v244, v244, v245
	v_mov_b32_e32 v245, v244
	v_max_f32_e32 v248, v197, v197
	s_nop 0
	v_permlane32_swap_b32_e32 v244, v245
	v_max_f32_e32 v244, v244, v245
	v_mul_f32_e32 v244, 0x3e38aa3b, v244
	v_max_f32_e32 v248, v248, v244
	v_cmp_gt_f32_e32 vcc, v248, v197
	s_cbranch_vccz .Lattn_p_nr0_a
	v_sub_f32_e32 v240, v197, v248
	v_exp_f32_e32 v240, v240
	v_mov_b32_e32 v197, v248
	v_mul_f32_e32 v196, v196, v240
	v_pk_mul_f32 v[64:65], v[64:65], v[240:241] op_sel_hi:[1,0]
	v_pk_mul_f32 v[62:63], v[62:63], v[240:241] op_sel_hi:[1,0]
	v_pk_mul_f32 v[60:61], v[60:61], v[240:241] op_sel_hi:[1,0]
	v_pk_mul_f32 v[58:59], v[58:59], v[240:241] op_sel_hi:[1,0]
	v_pk_mul_f32 v[56:57], v[56:57], v[240:241] op_sel_hi:[1,0]
	v_pk_mul_f32 v[54:55], v[54:55], v[240:241] op_sel_hi:[1,0]
	v_pk_mul_f32 v[52:53], v[52:53], v[240:241] op_sel_hi:[1,0]
	v_pk_mul_f32 v[50:51], v[50:51], v[240:241] op_sel_hi:[1,0]
	v_pk_mul_f32 v[48:49], v[48:49], v[240:241] op_sel_hi:[1,0]
	v_pk_mul_f32 v[46:47], v[46:47], v[240:241] op_sel_hi:[1,0]
	v_pk_mul_f32 v[44:45], v[44:45], v[240:241] op_sel_hi:[1,0]
	v_pk_mul_f32 v[42:43], v[42:43], v[240:241] op_sel_hi:[1,0]
	v_pk_mul_f32 v[40:41], v[40:41], v[240:241] op_sel_hi:[1,0]
	v_pk_mul_f32 v[38:39], v[38:39], v[240:241] op_sel_hi:[1,0]
	v_pk_mul_f32 v[36:37], v[36:37], v[240:241] op_sel_hi:[1,0]
	v_pk_mul_f32 v[34:35], v[34:35], v[240:241] op_sel_hi:[1,0]
; __device__ __forceinline__ unsigned cvt_pk_bf16(float lo, float hi) { unsigned r; asm("v_cvt_pk_bf16_f32 %0, %1, %2" : "=v"(r) : "v"(lo), "v"(hi)); return r; }
; __device__ __forceinline__ void attn_mfma(PP p, unsigned char* shm, int wv) {
;     ...
;                     float mx = s[0];
; #pragma unroll
;                     for (int i = 1; i < 16; ++i) mx = fmaxf(mx, s[i]);
;                     mx = fmaxf(mx, __shfl_xor(mx, 32));
;                     const float mnew = fmaxf(mrun[qi], mx * SC2);
;                     if (__builtin_amdgcn_ballot_w64(mnew > mrun[qi]) != 0ull) {
;                         const float alpha = __builtin_amdgcn_exp2f(mrun[qi] - mnew);
;                         lrun[qi] *= alpha;
; #pragma unroll
;                         for (int db = 0; db < 2; ++db)
; #pragma unroll
;                             for (int i = 0; i < 16; ++i) oacc[db][qi][i] *= alpha;
;                         mrun[qi] = mnew;
;                     }
;                     float ls = 0.f;
; #pragma unroll
;                     for (int i = 0; i < 16; ++i) { s[i] = __builtin_amdgcn_exp2f(__builtin_fmaf(s[i], SC2, -mnew)); ls += s[i]; }
;                     lrun[qi] += ls;
;                     bf16x8 pf[2];
; #pragma unroll
;                     for (int s2 = 0; s2 < 2; ++s2) {
;                         u32x4 w; w.x = cvt_pk_bf16(s[8 * s2 + 0], s[8 * s2 + 1]); w.y = cvt_pk_bf16(s[8 * s2 + 2], s[8 * s2 + 3]);
;                         w.z = cvt_pk_bf16(s[8 * s2 + 4], s[8 * s2 + 5]); w.w = cvt_pk_bf16(s[8 * s2 + 6], s[8 * s2 + 7]);
;                         pf[s2] = __builtin_bit_cast(bf16x8, w);
;                     }
; #pragma unroll
;                     for (int db = 0; db < 2; ++db)
; #pragma unroll
;                         for (int s2 = 0; s2 < 2; ++s2) oacc[db][qi] = __builtin_amdgcn_mfma_f32_32x32x16_bf16(vf[db][s2], pf[s2], oacc[db][qi], 0, 0, 0);
;                 }
.Lattn_p_nr0_a:
	v_fma_f32 v236, v66, s31, -v248
	v_fma_f32 v237, v67, s31, -v248
	v_fma_f32 v238, v68, s31, -v248
	v_fma_f32 v239, v69, s31, -v248
	v_exp_f32_e32 v66, v236
	v_exp_f32_e32 v67, v237
	v_exp_f32_e32 v68, v238
	v_exp_f32_e32 v69, v239
	v_mfma_f32_32x32x16_bf16 v[220:235], v[150:153], v[106:109], v[220:235]
	v_fma_f32 v236, v70, s31, -v248
	v_fma_f32 v237, v71, s31, -v248
	v_fma_f32 v238, v72, s31, -v248
	v_fma_f32 v239, v73, s31, -v248
	v_exp_f32_e32 v70, v236
	v_exp_f32_e32 v71, v237
	v_exp_f32_e32 v72, v238
	v_exp_f32_e32 v73, v239
	v_fma_f32 v236, v74, s31, -v248
	v_fma_f32 v237, v75, s31, -v248
	v_fma_f32 v238, v76, s31, -v248
	v_fma_f32 v239, v77, s31, -v248
	v_exp_f32_e32 v74, v236
	v_exp_f32_e32 v75, v237
	v_exp_f32_e32 v76, v238
	v_exp_f32_e32 v77, v239
	v_mfma_f32_32x32x16_bf16 v[220:235], v[146:149], v[110:113], v[220:235]
	ds_read_b128 v[158:161], v200
	ds_read_b128 v[154:157], v200 offset:32
	ds_read_b128 v[150:153], v200 offset:64
	ds_read_b128 v[146:149], v200 offset:96
	v_add_u32_e32 v200, 0x1200, v200
	v_fma_f32 v236, v78, s31, -v248
	v_fma_f32 v237, v79, s31, -v248
	v_fma_f32 v238, v80, s31, -v248
	v_fma_f32 v239, v81, s31, -v248
	v_exp_f32_e32 v78, v236
	v_exp_f32_e32 v79, v237
	v_exp_f32_e32 v80, v238
	v_exp_f32_e32 v81, v239
	v_cvt_pk_bf16_f32 v204, v66, v67
	v_cvt_pk_bf16_f32 v205, v68, v69
	v_cvt_pk_bf16_f32 v206, v70, v71
	v_cvt_pk_bf16_f32 v207, v72, v73
	v_cvt_pk_bf16_f32 v208, v74, v75
	v_cvt_pk_bf16_f32 v209, v76, v77
	v_cvt_pk_bf16_f32 v210, v78, v79
	v_cvt_pk_bf16_f32 v211, v80, v81
	s_waitcnt lgkmcnt(4)
	v_mfma_f32_32x32x16_bf16 v[50:65], v[142:145], v[204:207], v[50:65]
	v_add_f32_e32 v250, 0, v66
	v_add_f32_e32 v250, v67, v250
	v_add_f32_e32 v250, v68, v250
	v_add_f32_e32 v250, v69, v250
	v_add_f32_e32 v250, v70, v250
	v_add_f32_e32 v250, v71, v250
	v_add_f32_e32 v250, v72, v250
	v_add_f32_e32 v250, v73, v250
	v_mfma_f32_32x32x16_bf16 v[34:49], v[134:137], v[204:207], v[34:49]
	v_add_f32_e32 v250, v74, v250
	v_add_f32_e32 v250, v75, v250
	v_add_f32_e32 v250, v76, v250
	v_add_f32_e32 v250, v77, v250
	v_add_f32_e32 v250, v78, v250
	v_add_f32_e32 v250, v79, v250
	v_add_f32_e32 v250, v80, v250
	v_add_f32_e32 v250, v81, v250
	v_add_f32_e32 v196, v250, v196
	v_mfma_f32_32x32x16_bf16 v[50:65], v[138:141], v[208:211], v[50:65]
	v_max3_f32 v246, v220, v221, v222
	v_max3_f32 v247, v223, v224, v225
	v_max3_f32 v246, v246, v226, v227
	v_max3_f32 v247, v247, v228, v229
	v_max3_f32 v246, v246, v230, v231
	v_max3_f32 v247, v247, v232, v233
	v_mfma_f32_32x32x16_bf16 v[34:49], v[130:133], v[208:211], v[34:49]
	v_max3_f32 v246, v246, v234, v235
	v_max_f32_e32 v246, v246, v247
	v_mov_b32_e32 v247, v246
	v_max_f32_e32 v249, v198, v198
	s_nop 0
	v_permlane32_swap_b32_e32 v246, v247
	v_max_f32_e32 v246, v246, v247
	v_mul_f32_e32 v246, 0x3e38aa3b, v246
	v_max_f32_e32 v249, v249, v246
	v_cmp_gt_f32_e32 vcc, v249, v198
	s_cbranch_vccz .Lattn_p_nr1_a
	v_sub_f32_e32 v240, v198, v249
	v_exp_f32_e32 v240, v240
	v_mov_b32_e32 v198, v249
	v_mul_f32_e32 v1, v1, v240
	v_pk_mul_f32 v[32:33], v[32:33], v[240:241] op_sel_hi:[1,0]
	v_pk_mul_f32 v[30:31], v[30:31], v[240:241] op_sel_hi:[1,0]
	v_pk_mul_f32 v[28:29], v[28:29], v[240:241] op_sel_hi:[1,0]
	v_pk_mul_f32 v[26:27], v[26:27], v[240:241] op_sel_hi:[1,0]
	v_pk_mul_f32 v[24:25], v[24:25], v[240:241] op_sel_hi:[1,0]
	v_pk_mul_f32 v[22:23], v[22:23], v[240:241] op_sel_hi:[1,0]
	v_pk_mul_f32 v[20:21], v[20:21], v[240:241] op_sel_hi:[1,0]
	v_pk_mul_f32 v[18:19], v[18:19], v[240:241] op_sel_hi:[1,0]
	v_pk_mul_f32 v[16:17], v[16:17], v[240:241] op_sel_hi:[1,0]
	v_pk_mul_f32 v[14:15], v[14:15], v[240:241] op_sel_hi:[1,0]
	v_pk_mul_f32 v[12:13], v[12:13], v[240:241] op_sel_hi:[1,0]
	v_pk_mul_f32 v[10:11], v[10:11], v[240:241] op_sel_hi:[1,0]
	v_pk_mul_f32 v[8:9], v[8:9], v[240:241] op_sel_hi:[1,0]
	v_pk_mul_f32 v[6:7], v[6:7], v[240:241] op_sel_hi:[1,0]
	v_pk_mul_f32 v[4:5], v[4:5], v[240:241] op_sel_hi:[1,0]
	v_pk_mul_f32 v[2:3], v[2:3], v[240:241] op_sel_hi:[1,0]
.Lattn_p_nr1_a:
	s_waitcnt lgkmcnt(0)
	v_fma_f32 v236, v220, s31, -v249
	v_fma_f32 v237, v221, s31, -v249
	v_fma_f32 v238, v222, s31, -v249
	v_fma_f32 v239, v223, s31, -v249
	v_exp_f32_e32 v220, v236
	v_exp_f32_e32 v221, v237
	v_exp_f32_e32 v222, v238
	v_exp_f32_e32 v223, v239
	v_mfma_f32_32x32x16_bf16 v[66:81], v[158:161], v[82:85], 0
	v_fma_f32 v236, v224, s31, -v249
	v_fma_f32 v237, v225, s31, -v249
	v_fma_f32 v238, v226, s31, -v249
	v_fma_f32 v239, v227, s31, -v249
	v_exp_f32_e32 v224, v236
	v_exp_f32_e32 v225, v237
	v_exp_f32_e32 v226, v238
	v_exp_f32_e32 v227, v239
	v_mfma_f32_32x32x16_bf16 v[66:81], v[154:157], v[86:89], v[66:81]
	v_fma_f32 v236, v228, s31, -v249
	v_fma_f32 v237, v229, s31, -v249
	v_fma_f32 v238, v230, s31, -v249
	v_fma_f32 v239, v231, s31, -v249
	v_exp_f32_e32 v228, v236
	v_exp_f32_e32 v229, v237
	v_exp_f32_e32 v230, v238
	v_exp_f32_e32 v231, v239
	v_mfma_f32_32x32x16_bf16 v[66:81], v[150:153], v[90:93], v[66:81]
	v_fma_f32 v236, v232, s31, -v249
	v_fma_f32 v237, v233, s31, -v249
	v_fma_f32 v238, v234, s31, -v249
	v_fma_f32 v239, v235, s31, -v249
	v_exp_f32_e32 v232, v236
	v_exp_f32_e32 v233, v237
	v_exp_f32_e32 v234, v238
	v_exp_f32_e32 v235, v239
	v_mfma_f32_32x32x16_bf16 v[66:81], v[146:149], v[94:97], v[66:81]
	v_cvt_pk_bf16_f32 v212, v220, v221
	v_cvt_pk_bf16_f32 v213, v222, v223
	v_cvt_pk_bf16_f32 v214, v224, v225
	v_cvt_pk_bf16_f32 v215, v226, v227
	v_cvt_pk_bf16_f32 v216, v228, v229
	v_cvt_pk_bf16_f32 v217, v230, v231
	v_cvt_pk_bf16_f32 v218, v232, v233
	v_cvt_pk_bf16_f32 v219, v234, v235
	v_mfma_f32_32x32x16_bf16 v[18:33], v[142:145], v[212:215], v[18:33]
	v_add_f32_e32 v251, 0, v220
	v_add_f32_e32 v251, v221, v251
	v_add_f32_e32 v251, v222, v251
	v_add_f32_e32 v251, v223, v251
	v_add_f32_e32 v251, v224, v251
	v_mfma_f32_32x32x16_bf16 v[2:17], v[134:137], v[212:215], v[2:17]
	v_add_f32_e32 v251, v225, v251
	v_add_f32_e32 v251, v226, v251
	v_add_f32_e32 v251, v227, v251
	v_add_f32_e32 v251, v228, v251
	v_add_f32_e32 v251, v229, v251
	v_mfma_f32_32x32x16_bf16 v[18:33], v[138:141], v[216:219], v[18:33]
	v_add_f32_e32 v251, v230, v251
	v_add_f32_e32 v251, v231, v251
	v_add_f32_e32 v251, v232, v251
	v_add_f32_e32 v251, v233, v251
	v_mfma_f32_32x32x16_bf16 v[2:17], v[130:133], v[216:219], v[2:17]
	v_add_f32_e32 v251, v234, v251
	v_add_f32_e32 v251, v235, v251
	v_add_f32_e32 v1, v251, v1
	s_add_i32 s40, s40, 1
	s_cmp_lt_u32 s40, s20
	s_cbranch_scc1 .Lattn_p_loop

; __device__ __forceinline__ unsigned cvt_pk_bf16(float lo, float hi) { unsigned r; asm("v_cvt_pk_bf16_f32 %0, %1, %2" : "=v"(r) : "v"(lo), "v"(hi)); return r; }
; __device__ __forceinline__ void attn_mfma(PP p, unsigned char* shm, int wv) {
;     ...
;                     float ls = 0.f;
; #pragma unroll
;                     for (int i = 0; i < 16; ++i) { s[i] = __builtin_amdgcn_exp2f(__builtin_fmaf(s[i], SC2, -mnew)); ls += s[i]; }
;                     lrun[qi] += ls;
;                     bf16x8 pf[2];
; #pragma unroll
;                     for (int s2 = 0; s2 < 2; ++s2) {
;                         u32x4 w; w.x = cvt_pk_bf16(s[8 * s2 + 0], s[8 * s2 + 1]); w.y = cvt_pk_bf16(s[8 * s2 + 2], s[8 * s2 + 3]);
;                         w.z = cvt_pk_bf16(s[8 * s2 + 4], s[8 * s2 + 5]); w.w = cvt_pk_bf16(s[8 * s2 + 6], s[8 * s2 + 7]);
;                         pf[s2] = __builtin_bit_cast(bf16x8, w);
;                     }
; #pragma unroll
;                     for (int db = 0; db < 2; ++db)
; #pragma unroll
;                         for (int s2 = 0; s2 < 2; ++s2) oacc[db][qi] = __builtin_amdgcn_mfma_f32_32x32x16_bf16(vf[db][s2], pf[s2], oacc[db][qi], 0, 0, 0);
;                 }
.Lattn_p_nr0_b:
	v_fma_f32 v236, v66, s31, -v248
	v_fma_f32 v237, v67, s31, -v248
	v_fma_f32 v238, v68, s31, -v248
	v_fma_f32 v239, v69, s31, -v248
	v_exp_f32_e32 v66, v236
	v_exp_f32_e32 v67, v237
	v_exp_f32_e32 v68, v238
	v_exp_f32_e32 v69, v239
	v_mfma_f32_32x32x16_bf16 v[220:235], v[150:153], v[106:109], v[220:235]
	v_fma_f32 v236, v70, s31, -v248
	v_fma_f32 v237, v71, s31, -v248
	v_fma_f32 v238, v72, s31, -v248
	v_fma_f32 v239, v73, s31, -v248
	v_exp_f32_e32 v70, v236
	v_exp_f32_e32 v71, v237
	v_exp_f32_e32 v72, v238
	v_exp_f32_e32 v73, v239
	v_fma_f32 v236, v74, s31, -v248
	v_fma_f32 v237, v75, s31, -v248
	v_fma_f32 v238, v76, s31, -v248
	v_fma_f32 v239, v77, s31, -v248
	v_exp_f32_e32 v74, v236
	v_exp_f32_e32 v75, v237
	v_exp_f32_e32 v76, v238
	v_exp_f32_e32 v77, v239
	v_mfma_f32_32x32x16_bf16 v[220:235], v[146:149], v[110:113], v[220:235]
	v_fma_f32 v236, v78, s31, -v248
	v_fma_f32 v237, v79, s31, -v248
	v_fma_f32 v238, v80, s31, -v248
	v_fma_f32 v239, v81, s31, -v248
	v_exp_f32_e32 v78, v236
	v_exp_f32_e32 v79, v237
	v_exp_f32_e32 v80, v238
	v_exp_f32_e32 v81, v239
	v_cvt_pk_bf16_f32 v204, v66, v67
	v_cvt_pk_bf16_f32 v205, v68, v69
	v_cvt_pk_bf16_f32 v206, v70, v71
	v_cvt_pk_bf16_f32 v207, v72, v73
	v_cvt_pk_bf16_f32 v208, v74, v75
	v_cvt_pk_bf16_f32 v209, v76, v77
	v_cvt_pk_bf16_f32 v210, v78, v79
	v_cvt_pk_bf16_f32 v211, v80, v81
	s_waitcnt lgkmcnt(0)
	v_mfma_f32_32x32x16_bf16 v[50:65], v[142:145], v[204:207], v[50:65]
	v_add_f32_e32 v250, 0, v66
	v_add_f32_e32 v250, v67, v250
	v_add_f32_e32 v250, v68, v250
	v_add_f32_e32 v250, v69, v250
	v_add_f32_e32 v250, v70, v250
	v_add_f32_e32 v250, v71, v250
	v_add_f32_e32 v250, v72, v250
	v_add_f32_e32 v250, v73, v250
	v_mfma_f32_32x32x16_bf16 v[34:49], v[134:137], v[204:207], v[34:49]
	v_add_f32_e32 v250, v74, v250
	v_add_f32_e32 v250, v75, v250
	v_add_f32_e32 v250, v76, v250
	v_add_f32_e32 v250, v77, v250
	v_add_f32_e32 v250, v78, v250
	v_add_f32_e32 v250, v79, v250
	v_add_f32_e32 v250, v80, v250
	v_add_f32_e32 v250, v81, v250
	v_add_f32_e32 v196, v250, v196
	v_mfma_f32_32x32x16_bf16 v[50:65], v[138:141], v[208:211], v[50:65]
	v_max3_f32 v246, v220, v221, v222
	v_max3_f32 v247, v223, v224, v225
	v_max3_f32 v246, v246, v226, v227
	v_max3_f32 v247, v247, v228, v229
	v_max3_f32 v246, v246, v230, v231
	v_max3_f32 v247, v247, v232, v233
	v_mfma_f32_32x32x16_bf16 v[34:49], v[130:133], v[208:211], v[34:49]
	v_max3_f32 v246, v246, v234, v235
	v_max_f32_e32 v246, v246, v247
	v_mov_b32_e32 v247, v246
	v_max_f32_e32 v249, v198, v198
	s_nop 0
	v_permlane32_swap_b32_e32 v246, v247
	v_max_f32_e32 v246, v246, v247
	v_mul_f32_e32 v246, 0x3e38aa3b, v246
	v_max_f32_e32 v249, v249, v246
	v_cmp_gt_f32_e32 vcc, v249, v198
	s_cbranch_vccz .Lattn_p_nr1_b
	v_sub_f32_e32 v240, v198, v249
	v_exp_f32_e32 v240, v240
	v_mov_b32_e32 v198, v249
	v_mul_f32_e32 v1, v1, v240
	v_pk_mul_f32 v[32:33], v[32:33], v[240:241] op_sel_hi:[1,0]
	v_pk_mul_f32 v[30:31], v[30:31], v[240:241] op_sel_hi:[1,0]
	v_pk_mul_f32 v[28:29], v[28:29], v[240:241] op_sel_hi:[1,0]
	v_pk_mul_f32 v[26:27], v[26:27], v[240:241] op_sel_hi:[1,0]
	v_pk_mul_f32 v[24:25], v[24:25], v[240:241] op_sel_hi:[1,0]
	v_pk_mul_f32 v[22:23], v[22:23], v[240:241] op_sel_hi:[1,0]
	v_pk_mul_f32 v[20:21], v[20:21], v[240:241] op_sel_hi:[1,0]
	v_pk_mul_f32 v[18:19], v[18:19], v[240:241] op_sel_hi:[1,0]
	v_pk_mul_f32 v[16:17], v[16:17], v[240:241] op_sel_hi:[1,0]
	v_pk_mul_f32 v[14:15], v[14:15], v[240:241] op_sel_hi:[1,0]
	v_pk_mul_f32 v[12:13], v[12:13], v[240:241] op_sel_hi:[1,0]
	v_pk_mul_f32 v[10:11], v[10:11], v[240:241] op_sel_hi:[1,0]
	v_pk_mul_f32 v[8:9], v[8:9], v[240:241] op_sel_hi:[1,0]
	v_pk_mul_f32 v[6:7], v[6:7], v[240:241] op_sel_hi:[1,0]
	v_pk_mul_f32 v[4:5], v[4:5], v[240:241] op_sel_hi:[1,0]
	v_pk_mul_f32 v[2:3], v[2:3], v[240:241] op_sel_hi:[1,0]
.Lattn_p_nr1_b:
	v_fma_f32 v236, v220, s31, -v249
	v_fma_f32 v237, v221, s31, -v249
	v_fma_f32 v238, v222, s31, -v249
	v_fma_f32 v239, v223, s31, -v249
	v_exp_f32_e32 v220, v236
	v_exp_f32_e32 v221, v237
	v_exp_f32_e32 v222, v238
	v_exp_f32_e32 v223, v239
	v_fma_f32 v236, v224, s31, -v249
	v_fma_f32 v237, v225, s31, -v249
	v_fma_f32 v238, v226, s31, -v249
	v_fma_f32 v239, v227, s31, -v249
	v_exp_f32_e32 v224, v236
	v_exp_f32_e32 v225, v237
	v_exp_f32_e32 v226, v238
	v_exp_f32_e32 v227, v239
	v_fma_f32 v236, v228, s31, -v249
	v_fma_f32 v237, v229, s31, -v249
	v_fma_f32 v238, v230, s31, -v249
	v_fma_f32 v239, v231, s31, -v249
	v_exp_f32_e32 v228, v236
	v_exp_f32_e32 v229, v237
	v_exp_f32_e32 v230, v238
	v_exp_f32_e32 v231, v239
	v_fma_f32 v236, v232, s31, -v249
	v_fma_f32 v237, v233, s31, -v249
	v_fma_f32 v238, v234, s31, -v249
	v_fma_f32 v239, v235, s31, -v249
	v_exp_f32_e32 v232, v236
	v_exp_f32_e32 v233, v237
	v_exp_f32_e32 v234, v238
	v_exp_f32_e32 v235, v239
	v_cvt_pk_bf16_f32 v212, v220, v221
	v_cvt_pk_bf16_f32 v213, v222, v223
	v_cvt_pk_bf16_f32 v214, v224, v225
	v_cvt_pk_bf16_f32 v215, v226, v227
	v_cvt_pk_bf16_f32 v216, v228, v229
	v_cvt_pk_bf16_f32 v217, v230, v231
	v_cvt_pk_bf16_f32 v218, v232, v233
	v_cvt_pk_bf16_f32 v219, v234, v235
	v_mfma_f32_32x32x16_bf16 v[18:33], v[142:145], v[212:215], v[18:33]
	v_add_f32_e32 v251, 0, v220
	v_add_f32_e32 v251, v221, v251
	v_add_f32_e32 v251, v222, v251
	v_add_f32_e32 v251, v223, v251
	v_add_f32_e32 v251, v224, v251
	v_mfma_f32_32x32x16_bf16 v[2:17], v[134:137], v[212:215], v[2:17]
	v_add_f32_e32 v251, v225, v251
	v_add_f32_e32 v251, v226, v251
	v_add_f32_e32 v251, v227, v251
	v_add_f32_e32 v251, v228, v251
	v_add_f32_e32 v251, v229, v251
	v_mfma_f32_32x32x16_bf16 v[18:33], v[138:141], v[216:219], v[18:33]
	v_add_f32_e32 v251, v230, v251
	v_add_f32_e32 v251, v231, v251
	v_add_f32_e32 v251, v232, v251
	v_add_f32_e32 v251, v233, v251
	v_mfma_f32_32x32x16_bf16 v[2:17], v[130:133], v[216:219], v[2:17]
	v_add_f32_e32 v251, v234, v251
	v_add_f32_e32 v251, v235, v251
	v_add_f32_e32 v1, v251, v1
